# GLA chunk-state scan: double-buffered 12-position batches (next batch loads in flight while current batch is scanned)
# speedup vs baseline: 1.0022x; 1.0022x over previous
; __device__ __forceinline__ unsigned pk2(float lo, float hi) { f32x2 v = {lo, hi}; bf16x2_t b = __builtin_convertvector(v, bf16x2_t); return __builtin_bit_cast(unsigned, b); }
; __device__ __forceinline__ void gla_scan(bf16* U, const float* D, int gtid, int nthr) {
;     for (int idx = gtid; idx < 24 * 4096; idx += nthr) {
;         const int chain = idx >> 12, e = (idx & 4095) * 2, dk = e & 63;
;         unsigned* u = (unsigned*)(U + (size_t)chain * NCH * 8192 + e); const f32x2* d = (const f32x2*)(D + (size_t)chain * NCH * 64 + dk); f32x2 S = (f32x2){0.f, 0.f};
;         for (int p0 = 0; p0 < NCH; p0 += 12) {
;             unsigned uu[12]; f32x2 dd[12];
; #pragma unroll
;             for (int i = 0; i < 12; ++i) { uu[i] = u[(size_t)(p0 + i) * 4096]; dd[i] = d[(p0 + i) * 32]; }
; #pragma unroll
;             for (int i = 0; i < 12; ++i) { u[(size_t)(p0 + i) * 4096] = pk2(S.x, S.y); S.x = dd[i].x * S.x + bflo(uu[i]); S.y = dd[i].y * S.y + bfhi(uu[i]); }
.LBB0_601:
	s_waitcnt lgkmcnt(0)
	s_add_u32 s6, s8, 0x900000
	s_addc_u32 s7, s9, 0
	v_add_u32_e32 v70, 0x21100000, v0
	v_mov_b32_e32 v72, v2
	v_mov_b32_e32 v71, v70
	global_load_dword v80, v70, s[6:7]
	v_add_u32_e32 v70, 0x4000, v70
	global_load_dword v81, v70, s[6:7]
	v_add_u32_e32 v70, 0x4000, v70
	global_load_dword v82, v70, s[6:7]
	v_add_u32_e32 v70, 0x4000, v70
	global_load_dword v83, v70, s[6:7]
	v_add_u32_e32 v70, 0x4000, v70
	global_load_dword v84, v70, s[6:7]
	v_add_u32_e32 v70, 0x4000, v70
	global_load_dword v85, v70, s[6:7]
	v_add_u32_e32 v70, 0x4000, v70
	global_load_dword v86, v70, s[6:7]
	v_add_u32_e32 v70, 0x4000, v70
	global_load_dword v87, v70, s[6:7]
	v_add_u32_e32 v70, 0x4000, v70
	global_load_dword v88, v70, s[6:7]
	v_add_u32_e32 v70, 0x4000, v70
	global_load_dword v89, v70, s[6:7]
	v_add_u32_e32 v70, 0x4000, v70
	global_load_dword v90, v70, s[6:7]
	v_add_u32_e32 v70, 0x4000, v70
	global_load_dword v91, v70, s[6:7]
	v_add_u32_e32 v70, 0x4000, v70
	global_load_dwordx2 v[100:101], v72, s[6:7]
	global_load_dwordx2 v[102:103], v72, s[6:7] offset:256
	global_load_dwordx2 v[104:105], v72, s[6:7] offset:512
	global_load_dwordx2 v[106:107], v72, s[6:7] offset:768
	global_load_dwordx2 v[108:109], v72, s[6:7] offset:1024
	global_load_dwordx2 v[110:111], v72, s[6:7] offset:1280
	global_load_dwordx2 v[112:113], v72, s[6:7] offset:1536
	global_load_dwordx2 v[114:115], v72, s[6:7] offset:1792
	global_load_dwordx2 v[116:117], v72, s[6:7] offset:2048
	global_load_dwordx2 v[118:119], v72, s[6:7] offset:2304
	global_load_dwordx2 v[120:121], v72, s[6:7] offset:2560
	global_load_dwordx2 v[122:123], v72, s[6:7] offset:2816
	v_add_u32_e32 v72, 0xc00, v72
	global_load_dword v150, v70, s[6:7]
	v_add_u32_e32 v70, 0x4000, v70
	global_load_dword v151, v70, s[6:7]
	v_add_u32_e32 v70, 0x4000, v70
	global_load_dword v152, v70, s[6:7]
	v_add_u32_e32 v70, 0x4000, v70
	global_load_dword v153, v70, s[6:7]
	v_add_u32_e32 v70, 0x4000, v70
	global_load_dword v154, v70, s[6:7]
	v_add_u32_e32 v70, 0x4000, v70
	global_load_dword v155, v70, s[6:7]
	v_add_u32_e32 v70, 0x4000, v70
	global_load_dword v156, v70, s[6:7]
	v_add_u32_e32 v70, 0x4000, v70
	global_load_dword v157, v70, s[6:7]
	v_add_u32_e32 v70, 0x4000, v70
	global_load_dword v158, v70, s[6:7]
	v_add_u32_e32 v70, 0x4000, v70
	global_load_dword v159, v70, s[6:7]
	v_add_u32_e32 v70, 0x4000, v70
	global_load_dword v160, v70, s[6:7]
	v_add_u32_e32 v70, 0x4000, v70
	global_load_dword v161, v70, s[6:7]
	v_add_u32_e32 v70, 0x4000, v70
	global_load_dwordx2 v[174:175], v72, s[6:7]
	global_load_dwordx2 v[176:177], v72, s[6:7] offset:256
	global_load_dwordx2 v[178:179], v72, s[6:7] offset:512
	global_load_dwordx2 v[180:181], v72, s[6:7] offset:768
	global_load_dwordx2 v[182:183], v72, s[6:7] offset:1024
	global_load_dwordx2 v[184:185], v72, s[6:7] offset:1280
	global_load_dwordx2 v[186:187], v72, s[6:7] offset:1536
	global_load_dwordx2 v[188:189], v72, s[6:7] offset:1792
	global_load_dwordx2 v[190:191], v72, s[6:7] offset:2048
	global_load_dwordx2 v[192:193], v72, s[6:7] offset:2304
	global_load_dwordx2 v[194:195], v72, s[6:7] offset:2560
	global_load_dwordx2 v[196:197], v72, s[6:7] offset:2816
	v_add_u32_e32 v72, 0xc00, v72
	s_waitcnt vmcnt(24)
	v_cvt_pk_bf16_f32 v78, v4, v5
	v_lshlrev_b32_e32 v76, 16, v80
	v_and_b32_e32 v77, 0xffff0000, v80
	global_store_dword v71, v78, s[6:7]
	v_pk_fma_f32 v[4:5], v[4:5], v[100:101], v[76:77]
	v_add_u32_e32 v71, 0x4000, v71
	v_cvt_pk_bf16_f32 v78, v4, v5
	v_lshlrev_b32_e32 v76, 16, v81
	v_and_b32_e32 v77, 0xffff0000, v81
	global_store_dword v71, v78, s[6:7]
	v_pk_fma_f32 v[4:5], v[4:5], v[102:103], v[76:77]
	v_add_u32_e32 v71, 0x4000, v71
	v_cvt_pk_bf16_f32 v78, v4, v5
	v_lshlrev_b32_e32 v76, 16, v82
	v_and_b32_e32 v77, 0xffff0000, v82
	global_store_dword v71, v78, s[6:7]
	v_pk_fma_f32 v[4:5], v[4:5], v[104:105], v[76:77]
	v_add_u32_e32 v71, 0x4000, v71
	v_cvt_pk_bf16_f32 v78, v4, v5
	v_lshlrev_b32_e32 v76, 16, v83
	v_and_b32_e32 v77, 0xffff0000, v83
	global_store_dword v71, v78, s[6:7]
	v_pk_fma_f32 v[4:5], v[4:5], v[106:107], v[76:77]
	v_add_u32_e32 v71, 0x4000, v71
	v_cvt_pk_bf16_f32 v78, v4, v5
	v_lshlrev_b32_e32 v76, 16, v84
	v_and_b32_e32 v77, 0xffff0000, v84
	global_store_dword v71, v78, s[6:7]
	v_pk_fma_f32 v[4:5], v[4:5], v[108:109], v[76:77]
	v_add_u32_e32 v71, 0x4000, v71
	v_cvt_pk_bf16_f32 v78, v4, v5
	v_lshlrev_b32_e32 v76, 16, v85
	v_and_b32_e32 v77, 0xffff0000, v85
	global_store_dword v71, v78, s[6:7]
	v_pk_fma_f32 v[4:5], v[4:5], v[110:111], v[76:77]
	v_add_u32_e32 v71, 0x4000, v71
	v_cvt_pk_bf16_f32 v78, v4, v5
	v_lshlrev_b32_e32 v76, 16, v86
	v_and_b32_e32 v77, 0xffff0000, v86
	global_store_dword v71, v78, s[6:7]
	v_pk_fma_f32 v[4:5], v[4:5], v[112:113], v[76:77]
	v_add_u32_e32 v71, 0x4000, v71
	v_cvt_pk_bf16_f32 v78, v4, v5
	v_lshlrev_b32_e32 v76, 16, v87
	v_and_b32_e32 v77, 0xffff0000, v87
	global_store_dword v71, v78, s[6:7]
	v_pk_fma_f32 v[4:5], v[4:5], v[114:115], v[76:77]
	v_add_u32_e32 v71, 0x4000, v71
	v_cvt_pk_bf16_f32 v78, v4, v5
	v_lshlrev_b32_e32 v76, 16, v88
	v_and_b32_e32 v77, 0xffff0000, v88
	global_store_dword v71, v78, s[6:7]
	v_pk_fma_f32 v[4:5], v[4:5], v[116:117], v[76:77]
	v_add_u32_e32 v71, 0x4000, v71
	v_cvt_pk_bf16_f32 v78, v4, v5
	v_lshlrev_b32_e32 v76, 16, v89
	v_and_b32_e32 v77, 0xffff0000, v89
	global_store_dword v71, v78, s[6:7]
	v_pk_fma_f32 v[4:5], v[4:5], v[118:119], v[76:77]
	v_add_u32_e32 v71, 0x4000, v71
	v_cvt_pk_bf16_f32 v78, v4, v5
	v_lshlrev_b32_e32 v76, 16, v90
	v_and_b32_e32 v77, 0xffff0000, v90
	global_store_dword v71, v78, s[6:7]
	v_pk_fma_f32 v[4:5], v[4:5], v[120:121], v[76:77]
	v_add_u32_e32 v71, 0x4000, v71
; __device__ __forceinline__ unsigned pk2(float lo, float hi) { f32x2 v = {lo, hi}; bf16x2_t b = __builtin_convertvector(v, bf16x2_t); return __builtin_bit_cast(unsigned, b); }
; __device__ __forceinline__ void gla_scan(bf16* U, const float* D, int gtid, int nthr) {
;     ...
;         for (int p0 = 0; p0 < NCH; p0 += 12) {
;             unsigned uu[12]; f32x2 dd[12];
; #pragma unroll
;             for (int i = 0; i < 12; ++i) { uu[i] = u[(size_t)(p0 + i) * 4096]; dd[i] = d[(p0 + i) * 32]; }
; #pragma unroll
;             for (int i = 0; i < 12; ++i) { u[(size_t)(p0 + i) * 4096] = pk2(S.x, S.y); S.x = dd[i].x * S.x + bflo(uu[i]); S.y = dd[i].y * S.y + bfhi(uu[i]); }
	v_cvt_pk_bf16_f32 v78, v4, v5
	v_lshlrev_b32_e32 v76, 16, v91
	v_and_b32_e32 v77, 0xffff0000, v91
	global_store_dword v71, v78, s[6:7]
	v_pk_fma_f32 v[4:5], v[4:5], v[122:123], v[76:77]
	v_add_u32_e32 v71, 0x4000, v71
	global_load_dword v80, v70, s[6:7]
	v_add_u32_e32 v70, 0x4000, v70
	global_load_dword v81, v70, s[6:7]
	v_add_u32_e32 v70, 0x4000, v70
	global_load_dword v82, v70, s[6:7]
	v_add_u32_e32 v70, 0x4000, v70
	global_load_dword v83, v70, s[6:7]
	v_add_u32_e32 v70, 0x4000, v70
	global_load_dword v84, v70, s[6:7]
	v_add_u32_e32 v70, 0x4000, v70
	global_load_dword v85, v70, s[6:7]
	v_add_u32_e32 v70, 0x4000, v70
	global_load_dword v86, v70, s[6:7]
	v_add_u32_e32 v70, 0x4000, v70
	global_load_dword v87, v70, s[6:7]
	v_add_u32_e32 v70, 0x4000, v70
	global_load_dword v88, v70, s[6:7]
	v_add_u32_e32 v70, 0x4000, v70
	global_load_dword v89, v70, s[6:7]
	v_add_u32_e32 v70, 0x4000, v70
	global_load_dword v90, v70, s[6:7]
	v_add_u32_e32 v70, 0x4000, v70
	global_load_dword v91, v70, s[6:7]
	v_add_u32_e32 v70, 0x4000, v70
	global_load_dwordx2 v[100:101], v72, s[6:7]
	global_load_dwordx2 v[102:103], v72, s[6:7] offset:256
	global_load_dwordx2 v[104:105], v72, s[6:7] offset:512
	global_load_dwordx2 v[106:107], v72, s[6:7] offset:768
	global_load_dwordx2 v[108:109], v72, s[6:7] offset:1024
	global_load_dwordx2 v[110:111], v72, s[6:7] offset:1280
	global_load_dwordx2 v[112:113], v72, s[6:7] offset:1536
	global_load_dwordx2 v[114:115], v72, s[6:7] offset:1792
	global_load_dwordx2 v[116:117], v72, s[6:7] offset:2048
	global_load_dwordx2 v[118:119], v72, s[6:7] offset:2304
	global_load_dwordx2 v[120:121], v72, s[6:7] offset:2560
	global_load_dwordx2 v[122:123], v72, s[6:7] offset:2816
	v_add_u32_e32 v72, 0xc00, v72
	s_waitcnt vmcnt(36)
	v_cvt_pk_bf16_f32 v78, v4, v5
	v_lshlrev_b32_e32 v76, 16, v150
	v_and_b32_e32 v77, 0xffff0000, v150
	global_store_dword v71, v78, s[6:7]
	v_pk_fma_f32 v[4:5], v[4:5], v[174:175], v[76:77]
	v_add_u32_e32 v71, 0x4000, v71
	v_cvt_pk_bf16_f32 v78, v4, v5
	v_lshlrev_b32_e32 v76, 16, v151
	v_and_b32_e32 v77, 0xffff0000, v151
	global_store_dword v71, v78, s[6:7]
	v_pk_fma_f32 v[4:5], v[4:5], v[176:177], v[76:77]
	v_add_u32_e32 v71, 0x4000, v71
	v_cvt_pk_bf16_f32 v78, v4, v5
	v_lshlrev_b32_e32 v76, 16, v152
	v_and_b32_e32 v77, 0xffff0000, v152
	global_store_dword v71, v78, s[6:7]
	v_pk_fma_f32 v[4:5], v[4:5], v[178:179], v[76:77]
	v_add_u32_e32 v71, 0x4000, v71
	v_cvt_pk_bf16_f32 v78, v4, v5
	v_lshlrev_b32_e32 v76, 16, v153
	v_and_b32_e32 v77, 0xffff0000, v153
	global_store_dword v71, v78, s[6:7]
	v_pk_fma_f32 v[4:5], v[4:5], v[180:181], v[76:77]
	v_add_u32_e32 v71, 0x4000, v71
	v_cvt_pk_bf16_f32 v78, v4, v5
	v_lshlrev_b32_e32 v76, 16, v154
	v_and_b32_e32 v77, 0xffff0000, v154
	global_store_dword v71, v78, s[6:7]
	v_pk_fma_f32 v[4:5], v[4:5], v[182:183], v[76:77]
	v_add_u32_e32 v71, 0x4000, v71
	v_cvt_pk_bf16_f32 v78, v4, v5
	v_lshlrev_b32_e32 v76, 16, v155
	v_and_b32_e32 v77, 0xffff0000, v155
	global_store_dword v71, v78, s[6:7]
	v_pk_fma_f32 v[4:5], v[4:5], v[184:185], v[76:77]
	v_add_u32_e32 v71, 0x4000, v71
	v_cvt_pk_bf16_f32 v78, v4, v5
	v_lshlrev_b32_e32 v76, 16, v156
	v_and_b32_e32 v77, 0xffff0000, v156
	global_store_dword v71, v78, s[6:7]
	v_pk_fma_f32 v[4:5], v[4:5], v[186:187], v[76:77]
	v_add_u32_e32 v71, 0x4000, v71
	v_cvt_pk_bf16_f32 v78, v4, v5
	v_lshlrev_b32_e32 v76, 16, v157
	v_and_b32_e32 v77, 0xffff0000, v157
	global_store_dword v71, v78, s[6:7]
	v_pk_fma_f32 v[4:5], v[4:5], v[188:189], v[76:77]
	v_add_u32_e32 v71, 0x4000, v71
	v_cvt_pk_bf16_f32 v78, v4, v5
	v_lshlrev_b32_e32 v76, 16, v158
	v_and_b32_e32 v77, 0xffff0000, v158
	global_store_dword v71, v78, s[6:7]
	v_pk_fma_f32 v[4:5], v[4:5], v[190:191], v[76:77]
	v_add_u32_e32 v71, 0x4000, v71
	v_cvt_pk_bf16_f32 v78, v4, v5
	v_lshlrev_b32_e32 v76, 16, v159
	v_and_b32_e32 v77, 0xffff0000, v159
	global_store_dword v71, v78, s[6:7]
	v_pk_fma_f32 v[4:5], v[4:5], v[192:193], v[76:77]
	v_add_u32_e32 v71, 0x4000, v71
	v_cvt_pk_bf16_f32 v78, v4, v5
	v_lshlrev_b32_e32 v76, 16, v160
	v_and_b32_e32 v77, 0xffff0000, v160
	global_store_dword v71, v78, s[6:7]
	v_pk_fma_f32 v[4:5], v[4:5], v[194:195], v[76:77]
	v_add_u32_e32 v71, 0x4000, v71
	v_cvt_pk_bf16_f32 v78, v4, v5
	v_lshlrev_b32_e32 v76, 16, v161
	v_and_b32_e32 v77, 0xffff0000, v161
	global_store_dword v71, v78, s[6:7]
	v_pk_fma_f32 v[4:5], v[4:5], v[196:197], v[76:77]
	v_add_u32_e32 v71, 0x4000, v71
	global_load_dword v150, v70, s[6:7]
	v_add_u32_e32 v70, 0x4000, v70
	global_load_dword v151, v70, s[6:7]
	v_add_u32_e32 v70, 0x4000, v70
	global_load_dword v152, v70, s[6:7]
	v_add_u32_e32 v70, 0x4000, v70
	global_load_dword v153, v70, s[6:7]
	v_add_u32_e32 v70, 0x4000, v70
	global_load_dword v154, v70, s[6:7]
	v_add_u32_e32 v70, 0x4000, v70
	global_load_dword v155, v70, s[6:7]
	v_add_u32_e32 v70, 0x4000, v70
	global_load_dword v156, v70, s[6:7]
	v_add_u32_e32 v70, 0x4000, v70
	global_load_dword v157, v70, s[6:7]
	v_add_u32_e32 v70, 0x4000, v70
	global_load_dword v158, v70, s[6:7]
	v_add_u32_e32 v70, 0x4000, v70
	global_load_dword v159, v70, s[6:7]
	v_add_u32_e32 v70, 0x4000, v70
	global_load_dword v160, v70, s[6:7]
	v_add_u32_e32 v70, 0x4000, v70
	global_load_dword v161, v70, s[6:7]
	v_add_u32_e32 v70, 0x4000, v70
	global_load_dwordx2 v[174:175], v72, s[6:7]
	global_load_dwordx2 v[176:177], v72, s[6:7] offset:256
	global_load_dwordx2 v[178:179], v72, s[6:7] offset:512
	global_load_dwordx2 v[180:181], v72, s[6:7] offset:768
	global_load_dwordx2 v[182:183], v72, s[6:7] offset:1024
	global_load_dwordx2 v[184:185], v72, s[6:7] offset:1280
	global_load_dwordx2 v[186:187], v72, s[6:7] offset:1536
	global_load_dwordx2 v[188:189], v72, s[6:7] offset:1792
	global_load_dwordx2 v[190:191], v72, s[6:7] offset:2048
	global_load_dwordx2 v[192:193], v72, s[6:7] offset:2304
	global_load_dwordx2 v[194:195], v72, s[6:7] offset:2560
	global_load_dwordx2 v[196:197], v72, s[6:7] offset:2816
	v_add_u32_e32 v72, 0xc00, v72
	s_waitcnt vmcnt(36)
; __device__ __forceinline__ unsigned pk2(float lo, float hi) { f32x2 v = {lo, hi}; bf16x2_t b = __builtin_convertvector(v, bf16x2_t); return __builtin_bit_cast(unsigned, b); }
; __device__ __forceinline__ void gla_scan(bf16* U, const float* D, int gtid, int nthr) {
;     ...
;         for (int p0 = 0; p0 < NCH; p0 += 12) {
;             unsigned uu[12]; f32x2 dd[12];
; #pragma unroll
;             for (int i = 0; i < 12; ++i) { uu[i] = u[(size_t)(p0 + i) * 4096]; dd[i] = d[(p0 + i) * 32]; }
; #pragma unroll
;             for (int i = 0; i < 12; ++i) { u[(size_t)(p0 + i) * 4096] = pk2(S.x, S.y); S.x = dd[i].x * S.x + bflo(uu[i]); S.y = dd[i].y * S.y + bfhi(uu[i]); }
	v_cvt_pk_bf16_f32 v78, v4, v5
	v_lshlrev_b32_e32 v76, 16, v80
	v_and_b32_e32 v77, 0xffff0000, v80
	global_store_dword v71, v78, s[6:7]
	v_pk_fma_f32 v[4:5], v[4:5], v[100:101], v[76:77]
	v_add_u32_e32 v71, 0x4000, v71
	v_cvt_pk_bf16_f32 v78, v4, v5
	v_lshlrev_b32_e32 v76, 16, v81
	v_and_b32_e32 v77, 0xffff0000, v81
	global_store_dword v71, v78, s[6:7]
	v_pk_fma_f32 v[4:5], v[4:5], v[102:103], v[76:77]
	v_add_u32_e32 v71, 0x4000, v71
	v_cvt_pk_bf16_f32 v78, v4, v5
	v_lshlrev_b32_e32 v76, 16, v82
	v_and_b32_e32 v77, 0xffff0000, v82
	global_store_dword v71, v78, s[6:7]
	v_pk_fma_f32 v[4:5], v[4:5], v[104:105], v[76:77]
	v_add_u32_e32 v71, 0x4000, v71
	v_cvt_pk_bf16_f32 v78, v4, v5
	v_lshlrev_b32_e32 v76, 16, v83
	v_and_b32_e32 v77, 0xffff0000, v83
	global_store_dword v71, v78, s[6:7]
	v_pk_fma_f32 v[4:5], v[4:5], v[106:107], v[76:77]
	v_add_u32_e32 v71, 0x4000, v71
	v_cvt_pk_bf16_f32 v78, v4, v5
	v_lshlrev_b32_e32 v76, 16, v84
	v_and_b32_e32 v77, 0xffff0000, v84
	global_store_dword v71, v78, s[6:7]
	v_pk_fma_f32 v[4:5], v[4:5], v[108:109], v[76:77]
	v_add_u32_e32 v71, 0x4000, v71
	v_cvt_pk_bf16_f32 v78, v4, v5
	v_lshlrev_b32_e32 v76, 16, v85
	v_and_b32_e32 v77, 0xffff0000, v85
	global_store_dword v71, v78, s[6:7]
	v_pk_fma_f32 v[4:5], v[4:5], v[110:111], v[76:77]
	v_add_u32_e32 v71, 0x4000, v71
	v_cvt_pk_bf16_f32 v78, v4, v5
	v_lshlrev_b32_e32 v76, 16, v86
	v_and_b32_e32 v77, 0xffff0000, v86
	global_store_dword v71, v78, s[6:7]
	v_pk_fma_f32 v[4:5], v[4:5], v[112:113], v[76:77]
	v_add_u32_e32 v71, 0x4000, v71
	v_cvt_pk_bf16_f32 v78, v4, v5
	v_lshlrev_b32_e32 v76, 16, v87
	v_and_b32_e32 v77, 0xffff0000, v87
	global_store_dword v71, v78, s[6:7]
	v_pk_fma_f32 v[4:5], v[4:5], v[114:115], v[76:77]
	v_add_u32_e32 v71, 0x4000, v71
	v_cvt_pk_bf16_f32 v78, v4, v5
	v_lshlrev_b32_e32 v76, 16, v88
	v_and_b32_e32 v77, 0xffff0000, v88
	global_store_dword v71, v78, s[6:7]
	v_pk_fma_f32 v[4:5], v[4:5], v[116:117], v[76:77]
	v_add_u32_e32 v71, 0x4000, v71
	v_cvt_pk_bf16_f32 v78, v4, v5
	v_lshlrev_b32_e32 v76, 16, v89
	v_and_b32_e32 v77, 0xffff0000, v89
	global_store_dword v71, v78, s[6:7]
	v_pk_fma_f32 v[4:5], v[4:5], v[118:119], v[76:77]
	v_add_u32_e32 v71, 0x4000, v71
	v_cvt_pk_bf16_f32 v78, v4, v5
	v_lshlrev_b32_e32 v76, 16, v90
	v_and_b32_e32 v77, 0xffff0000, v90
	global_store_dword v71, v78, s[6:7]
	v_pk_fma_f32 v[4:5], v[4:5], v[120:121], v[76:77]
	v_add_u32_e32 v71, 0x4000, v71
	v_cvt_pk_bf16_f32 v78, v4, v5
	v_lshlrev_b32_e32 v76, 16, v91
	v_and_b32_e32 v77, 0xffff0000, v91
	global_store_dword v71, v78, s[6:7]
	v_pk_fma_f32 v[4:5], v[4:5], v[122:123], v[76:77]
	v_add_u32_e32 v71, 0x4000, v71
	global_load_dword v80, v70, s[6:7]
	v_add_u32_e32 v70, 0x4000, v70
	global_load_dword v81, v70, s[6:7]
	v_add_u32_e32 v70, 0x4000, v70
	global_load_dword v82, v70, s[6:7]
	v_add_u32_e32 v70, 0x4000, v70
	global_load_dword v83, v70, s[6:7]
	v_add_u32_e32 v70, 0x4000, v70
	global_load_dword v84, v70, s[6:7]
	v_add_u32_e32 v70, 0x4000, v70
	global_load_dword v85, v70, s[6:7]
	v_add_u32_e32 v70, 0x4000, v70
	global_load_dword v86, v70, s[6:7]
	v_add_u32_e32 v70, 0x4000, v70
	global_load_dword v87, v70, s[6:7]
	v_add_u32_e32 v70, 0x4000, v70
	global_load_dword v88, v70, s[6:7]
	v_add_u32_e32 v70, 0x4000, v70
	global_load_dword v89, v70, s[6:7]
	v_add_u32_e32 v70, 0x4000, v70
	global_load_dword v90, v70, s[6:7]
	v_add_u32_e32 v70, 0x4000, v70
	global_load_dword v91, v70, s[6:7]
	v_add_u32_e32 v70, 0x4000, v70
	global_load_dwordx2 v[100:101], v72, s[6:7]
	global_load_dwordx2 v[102:103], v72, s[6:7] offset:256
	global_load_dwordx2 v[104:105], v72, s[6:7] offset:512
	global_load_dwordx2 v[106:107], v72, s[6:7] offset:768
	global_load_dwordx2 v[108:109], v72, s[6:7] offset:1024
	global_load_dwordx2 v[110:111], v72, s[6:7] offset:1280
	global_load_dwordx2 v[112:113], v72, s[6:7] offset:1536
	global_load_dwordx2 v[114:115], v72, s[6:7] offset:1792
	global_load_dwordx2 v[116:117], v72, s[6:7] offset:2048
	global_load_dwordx2 v[118:119], v72, s[6:7] offset:2304
	global_load_dwordx2 v[120:121], v72, s[6:7] offset:2560
	global_load_dwordx2 v[122:123], v72, s[6:7] offset:2816
	v_add_u32_e32 v72, 0xc00, v72
	s_waitcnt vmcnt(36)
	v_cvt_pk_bf16_f32 v78, v4, v5
	v_lshlrev_b32_e32 v76, 16, v150
	v_and_b32_e32 v77, 0xffff0000, v150
	global_store_dword v71, v78, s[6:7]
	v_pk_fma_f32 v[4:5], v[4:5], v[174:175], v[76:77]
	v_add_u32_e32 v71, 0x4000, v71
	v_cvt_pk_bf16_f32 v78, v4, v5
	v_lshlrev_b32_e32 v76, 16, v151
	v_and_b32_e32 v77, 0xffff0000, v151
	global_store_dword v71, v78, s[6:7]
	v_pk_fma_f32 v[4:5], v[4:5], v[176:177], v[76:77]
	v_add_u32_e32 v71, 0x4000, v71
	v_cvt_pk_bf16_f32 v78, v4, v5
	v_lshlrev_b32_e32 v76, 16, v152
	v_and_b32_e32 v77, 0xffff0000, v152
	global_store_dword v71, v78, s[6:7]
	v_pk_fma_f32 v[4:5], v[4:5], v[178:179], v[76:77]
	v_add_u32_e32 v71, 0x4000, v71
	v_cvt_pk_bf16_f32 v78, v4, v5
	v_lshlrev_b32_e32 v76, 16, v153
	v_and_b32_e32 v77, 0xffff0000, v153
	global_store_dword v71, v78, s[6:7]
	v_pk_fma_f32 v[4:5], v[4:5], v[180:181], v[76:77]
	v_add_u32_e32 v71, 0x4000, v71
	v_cvt_pk_bf16_f32 v78, v4, v5
	v_lshlrev_b32_e32 v76, 16, v154
	v_and_b32_e32 v77, 0xffff0000, v154
	global_store_dword v71, v78, s[6:7]
	v_pk_fma_f32 v[4:5], v[4:5], v[182:183], v[76:77]
	v_add_u32_e32 v71, 0x4000, v71
	v_cvt_pk_bf16_f32 v78, v4, v5
	v_lshlrev_b32_e32 v76, 16, v155
	v_and_b32_e32 v77, 0xffff0000, v155
	global_store_dword v71, v78, s[6:7]
	v_pk_fma_f32 v[4:5], v[4:5], v[184:185], v[76:77]
	v_add_u32_e32 v71, 0x4000, v71
	v_cvt_pk_bf16_f32 v78, v4, v5
	v_lshlrev_b32_e32 v76, 16, v156
	v_and_b32_e32 v77, 0xffff0000, v156
	global_store_dword v71, v78, s[6:7]
; __device__ __forceinline__ unsigned pk2(float lo, float hi) { f32x2 v = {lo, hi}; bf16x2_t b = __builtin_convertvector(v, bf16x2_t); return __builtin_bit_cast(unsigned, b); }
; __device__ __forceinline__ void gla_scan(bf16* U, const float* D, int gtid, int nthr) {
;     ...
;         for (int p0 = 0; p0 < NCH; p0 += 12) {
;             unsigned uu[12]; f32x2 dd[12];
; #pragma unroll
;             for (int i = 0; i < 12; ++i) { uu[i] = u[(size_t)(p0 + i) * 4096]; dd[i] = d[(p0 + i) * 32]; }
; #pragma unroll
;             for (int i = 0; i < 12; ++i) { u[(size_t)(p0 + i) * 4096] = pk2(S.x, S.y); S.x = dd[i].x * S.x + bflo(uu[i]); S.y = dd[i].y * S.y + bfhi(uu[i]); }
	v_pk_fma_f32 v[4:5], v[4:5], v[186:187], v[76:77]
	v_add_u32_e32 v71, 0x4000, v71
	v_cvt_pk_bf16_f32 v78, v4, v5
	v_lshlrev_b32_e32 v76, 16, v157
	v_and_b32_e32 v77, 0xffff0000, v157
	global_store_dword v71, v78, s[6:7]
	v_pk_fma_f32 v[4:5], v[4:5], v[188:189], v[76:77]
	v_add_u32_e32 v71, 0x4000, v71
	v_cvt_pk_bf16_f32 v78, v4, v5
	v_lshlrev_b32_e32 v76, 16, v158
	v_and_b32_e32 v77, 0xffff0000, v158
	global_store_dword v71, v78, s[6:7]
	v_pk_fma_f32 v[4:5], v[4:5], v[190:191], v[76:77]
	v_add_u32_e32 v71, 0x4000, v71
	v_cvt_pk_bf16_f32 v78, v4, v5
	v_lshlrev_b32_e32 v76, 16, v159
	v_and_b32_e32 v77, 0xffff0000, v159
	global_store_dword v71, v78, s[6:7]
	v_pk_fma_f32 v[4:5], v[4:5], v[192:193], v[76:77]
	v_add_u32_e32 v71, 0x4000, v71
	v_cvt_pk_bf16_f32 v78, v4, v5
	v_lshlrev_b32_e32 v76, 16, v160
	v_and_b32_e32 v77, 0xffff0000, v160
	global_store_dword v71, v78, s[6:7]
	v_pk_fma_f32 v[4:5], v[4:5], v[194:195], v[76:77]
	v_add_u32_e32 v71, 0x4000, v71
	v_cvt_pk_bf16_f32 v78, v4, v5
	v_lshlrev_b32_e32 v76, 16, v161
	v_and_b32_e32 v77, 0xffff0000, v161
	global_store_dword v71, v78, s[6:7]
	v_pk_fma_f32 v[4:5], v[4:5], v[196:197], v[76:77]
	v_add_u32_e32 v71, 0x4000, v71
	global_load_dword v150, v70, s[6:7]
	v_add_u32_e32 v70, 0x4000, v70
	global_load_dword v151, v70, s[6:7]
	v_add_u32_e32 v70, 0x4000, v70
	global_load_dword v152, v70, s[6:7]
	v_add_u32_e32 v70, 0x4000, v70
	global_load_dword v153, v70, s[6:7]
	v_add_u32_e32 v70, 0x4000, v70
	global_load_dword v154, v70, s[6:7]
	v_add_u32_e32 v70, 0x4000, v70
	global_load_dword v155, v70, s[6:7]
	v_add_u32_e32 v70, 0x4000, v70
	global_load_dword v156, v70, s[6:7]
	v_add_u32_e32 v70, 0x4000, v70
	global_load_dword v157, v70, s[6:7]
	v_add_u32_e32 v70, 0x4000, v70
	global_load_dword v158, v70, s[6:7]
	v_add_u32_e32 v70, 0x4000, v70
	global_load_dword v159, v70, s[6:7]
	v_add_u32_e32 v70, 0x4000, v70
	global_load_dword v160, v70, s[6:7]
	v_add_u32_e32 v70, 0x4000, v70
	global_load_dword v161, v70, s[6:7]
	v_add_u32_e32 v70, 0x4000, v70
	global_load_dwordx2 v[174:175], v72, s[6:7]
	global_load_dwordx2 v[176:177], v72, s[6:7] offset:256
	global_load_dwordx2 v[178:179], v72, s[6:7] offset:512
	global_load_dwordx2 v[180:181], v72, s[6:7] offset:768
	global_load_dwordx2 v[182:183], v72, s[6:7] offset:1024
	global_load_dwordx2 v[184:185], v72, s[6:7] offset:1280
	global_load_dwordx2 v[186:187], v72, s[6:7] offset:1536
	global_load_dwordx2 v[188:189], v72, s[6:7] offset:1792
	global_load_dwordx2 v[190:191], v72, s[6:7] offset:2048
	global_load_dwordx2 v[192:193], v72, s[6:7] offset:2304
	global_load_dwordx2 v[194:195], v72, s[6:7] offset:2560
	global_load_dwordx2 v[196:197], v72, s[6:7] offset:2816
	v_add_u32_e32 v72, 0xc00, v72
	s_waitcnt vmcnt(36)
	v_cvt_pk_bf16_f32 v78, v4, v5
	v_lshlrev_b32_e32 v76, 16, v80
	v_and_b32_e32 v77, 0xffff0000, v80
	global_store_dword v71, v78, s[6:7]
	v_pk_fma_f32 v[4:5], v[4:5], v[100:101], v[76:77]
	v_add_u32_e32 v71, 0x4000, v71
	v_cvt_pk_bf16_f32 v78, v4, v5
	v_lshlrev_b32_e32 v76, 16, v81
	v_and_b32_e32 v77, 0xffff0000, v81
	global_store_dword v71, v78, s[6:7]
	v_pk_fma_f32 v[4:5], v[4:5], v[102:103], v[76:77]
	v_add_u32_e32 v71, 0x4000, v71
	v_cvt_pk_bf16_f32 v78, v4, v5
	v_lshlrev_b32_e32 v76, 16, v82
	v_and_b32_e32 v77, 0xffff0000, v82
	global_store_dword v71, v78, s[6:7]
	v_pk_fma_f32 v[4:5], v[4:5], v[104:105], v[76:77]
	v_add_u32_e32 v71, 0x4000, v71
	v_cvt_pk_bf16_f32 v78, v4, v5
	v_lshlrev_b32_e32 v76, 16, v83
	v_and_b32_e32 v77, 0xffff0000, v83
	global_store_dword v71, v78, s[6:7]
	v_pk_fma_f32 v[4:5], v[4:5], v[106:107], v[76:77]
	v_add_u32_e32 v71, 0x4000, v71
	v_cvt_pk_bf16_f32 v78, v4, v5
	v_lshlrev_b32_e32 v76, 16, v84
	v_and_b32_e32 v77, 0xffff0000, v84
	global_store_dword v71, v78, s[6:7]
	v_pk_fma_f32 v[4:5], v[4:5], v[108:109], v[76:77]
	v_add_u32_e32 v71, 0x4000, v71
	v_cvt_pk_bf16_f32 v78, v4, v5
	v_lshlrev_b32_e32 v76, 16, v85
	v_and_b32_e32 v77, 0xffff0000, v85
	global_store_dword v71, v78, s[6:7]
	v_pk_fma_f32 v[4:5], v[4:5], v[110:111], v[76:77]
	v_add_u32_e32 v71, 0x4000, v71
	v_cvt_pk_bf16_f32 v78, v4, v5
	v_lshlrev_b32_e32 v76, 16, v86
	v_and_b32_e32 v77, 0xffff0000, v86
	global_store_dword v71, v78, s[6:7]
	v_pk_fma_f32 v[4:5], v[4:5], v[112:113], v[76:77]
	v_add_u32_e32 v71, 0x4000, v71
	v_cvt_pk_bf16_f32 v78, v4, v5
	v_lshlrev_b32_e32 v76, 16, v87
	v_and_b32_e32 v77, 0xffff0000, v87
	global_store_dword v71, v78, s[6:7]
	v_pk_fma_f32 v[4:5], v[4:5], v[114:115], v[76:77]
	v_add_u32_e32 v71, 0x4000, v71
	v_cvt_pk_bf16_f32 v78, v4, v5
	v_lshlrev_b32_e32 v76, 16, v88
	v_and_b32_e32 v77, 0xffff0000, v88
	global_store_dword v71, v78, s[6:7]
	v_pk_fma_f32 v[4:5], v[4:5], v[116:117], v[76:77]
	v_add_u32_e32 v71, 0x4000, v71
	v_cvt_pk_bf16_f32 v78, v4, v5
	v_lshlrev_b32_e32 v76, 16, v89
	v_and_b32_e32 v77, 0xffff0000, v89
	global_store_dword v71, v78, s[6:7]
	v_pk_fma_f32 v[4:5], v[4:5], v[118:119], v[76:77]
	v_add_u32_e32 v71, 0x4000, v71
	v_cvt_pk_bf16_f32 v78, v4, v5
	v_lshlrev_b32_e32 v76, 16, v90
	v_and_b32_e32 v77, 0xffff0000, v90
	global_store_dword v71, v78, s[6:7]
	v_pk_fma_f32 v[4:5], v[4:5], v[120:121], v[76:77]
	v_add_u32_e32 v71, 0x4000, v71
	v_cvt_pk_bf16_f32 v78, v4, v5
	v_lshlrev_b32_e32 v76, 16, v91
	v_and_b32_e32 v77, 0xffff0000, v91
	global_store_dword v71, v78, s[6:7]
	v_pk_fma_f32 v[4:5], v[4:5], v[122:123], v[76:77]
	v_add_u32_e32 v71, 0x4000, v71
	global_load_dword v80, v70, s[6:7]
	v_add_u32_e32 v70, 0x4000, v70
	global_load_dword v81, v70, s[6:7]
	v_add_u32_e32 v70, 0x4000, v70
	global_load_dword v82, v70, s[6:7]
	v_add_u32_e32 v70, 0x4000, v70
	global_load_dword v83, v70, s[6:7]
	v_add_u32_e32 v70, 0x4000, v70
	global_load_dword v84, v70, s[6:7]
	v_add_u32_e32 v70, 0x4000, v70
	global_load_dword v85, v70, s[6:7]
	v_add_u32_e32 v70, 0x4000, v70
	global_load_dword v86, v70, s[6:7]
	v_add_u32_e32 v70, 0x4000, v70
	global_load_dword v87, v70, s[6:7]
	v_add_u32_e32 v70, 0x4000, v70
	global_load_dword v88, v70, s[6:7]
	v_add_u32_e32 v70, 0x4000, v70
	global_load_dword v89, v70, s[6:7]
	v_add_u32_e32 v70, 0x4000, v70
	global_load_dword v90, v70, s[6:7]
	v_add_u32_e32 v70, 0x4000, v70
	global_load_dword v91, v70, s[6:7]
	v_add_u32_e32 v70, 0x4000, v70
	global_load_dwordx2 v[100:101], v72, s[6:7]
	global_load_dwordx2 v[102:103], v72, s[6:7] offset:256
	global_load_dwordx2 v[104:105], v72, s[6:7] offset:512
	global_load_dwordx2 v[106:107], v72, s[6:7] offset:768
	global_load_dwordx2 v[108:109], v72, s[6:7] offset:1024
	global_load_dwordx2 v[110:111], v72, s[6:7] offset:1280
	global_load_dwordx2 v[112:113], v72, s[6:7] offset:1536
	global_load_dwordx2 v[114:115], v72, s[6:7] offset:1792
	global_load_dwordx2 v[116:117], v72, s[6:7] offset:2048
	global_load_dwordx2 v[118:119], v72, s[6:7] offset:2304
	global_load_dwordx2 v[120:121], v72, s[6:7] offset:2560
	global_load_dwordx2 v[122:123], v72, s[6:7] offset:2816
	v_add_u32_e32 v72, 0xc00, v72
	s_waitcnt vmcnt(36)
; __device__ __forceinline__ unsigned pk2(float lo, float hi) { f32x2 v = {lo, hi}; bf16x2_t b = __builtin_convertvector(v, bf16x2_t); return __builtin_bit_cast(unsigned, b); }
; __device__ __forceinline__ void gla_scan(bf16* U, const float* D, int gtid, int nthr) {
;     ...
;         for (int p0 = 0; p0 < NCH; p0 += 12) {
;             unsigned uu[12]; f32x2 dd[12];
; #pragma unroll
;             for (int i = 0; i < 12; ++i) { uu[i] = u[(size_t)(p0 + i) * 4096]; dd[i] = d[(p0 + i) * 32]; }
; #pragma unroll
;             for (int i = 0; i < 12; ++i) { u[(size_t)(p0 + i) * 4096] = pk2(S.x, S.y); S.x = dd[i].x * S.x + bflo(uu[i]); S.y = dd[i].y * S.y + bfhi(uu[i]); }
	v_cvt_pk_bf16_f32 v78, v4, v5
	v_lshlrev_b32_e32 v76, 16, v150
	v_and_b32_e32 v77, 0xffff0000, v150
	global_store_dword v71, v78, s[6:7]
	v_pk_fma_f32 v[4:5], v[4:5], v[174:175], v[76:77]
	v_add_u32_e32 v71, 0x4000, v71
	v_cvt_pk_bf16_f32 v78, v4, v5
	v_lshlrev_b32_e32 v76, 16, v151
	v_and_b32_e32 v77, 0xffff0000, v151
	global_store_dword v71, v78, s[6:7]
	v_pk_fma_f32 v[4:5], v[4:5], v[176:177], v[76:77]
	v_add_u32_e32 v71, 0x4000, v71
	v_cvt_pk_bf16_f32 v78, v4, v5
	v_lshlrev_b32_e32 v76, 16, v152
	v_and_b32_e32 v77, 0xffff0000, v152
	global_store_dword v71, v78, s[6:7]
	v_pk_fma_f32 v[4:5], v[4:5], v[178:179], v[76:77]
	v_add_u32_e32 v71, 0x4000, v71
	v_cvt_pk_bf16_f32 v78, v4, v5
	v_lshlrev_b32_e32 v76, 16, v153
	v_and_b32_e32 v77, 0xffff0000, v153
	global_store_dword v71, v78, s[6:7]
	v_pk_fma_f32 v[4:5], v[4:5], v[180:181], v[76:77]
	v_add_u32_e32 v71, 0x4000, v71
	v_cvt_pk_bf16_f32 v78, v4, v5
	v_lshlrev_b32_e32 v76, 16, v154
	v_and_b32_e32 v77, 0xffff0000, v154
	global_store_dword v71, v78, s[6:7]
	v_pk_fma_f32 v[4:5], v[4:5], v[182:183], v[76:77]
	v_add_u32_e32 v71, 0x4000, v71
	v_cvt_pk_bf16_f32 v78, v4, v5
	v_lshlrev_b32_e32 v76, 16, v155
	v_and_b32_e32 v77, 0xffff0000, v155
	global_store_dword v71, v78, s[6:7]
	v_pk_fma_f32 v[4:5], v[4:5], v[184:185], v[76:77]
	v_add_u32_e32 v71, 0x4000, v71
	v_cvt_pk_bf16_f32 v78, v4, v5
	v_lshlrev_b32_e32 v76, 16, v156
	v_and_b32_e32 v77, 0xffff0000, v156
	global_store_dword v71, v78, s[6:7]
	v_pk_fma_f32 v[4:5], v[4:5], v[186:187], v[76:77]
	v_add_u32_e32 v71, 0x4000, v71
	v_cvt_pk_bf16_f32 v78, v4, v5
	v_lshlrev_b32_e32 v76, 16, v157
	v_and_b32_e32 v77, 0xffff0000, v157
	global_store_dword v71, v78, s[6:7]
	v_pk_fma_f32 v[4:5], v[4:5], v[188:189], v[76:77]
	v_add_u32_e32 v71, 0x4000, v71
	v_cvt_pk_bf16_f32 v78, v4, v5
	v_lshlrev_b32_e32 v76, 16, v158
	v_and_b32_e32 v77, 0xffff0000, v158
	global_store_dword v71, v78, s[6:7]
	v_pk_fma_f32 v[4:5], v[4:5], v[190:191], v[76:77]
	v_add_u32_e32 v71, 0x4000, v71
	v_cvt_pk_bf16_f32 v78, v4, v5
	v_lshlrev_b32_e32 v76, 16, v159
	v_and_b32_e32 v77, 0xffff0000, v159
	global_store_dword v71, v78, s[6:7]
	v_pk_fma_f32 v[4:5], v[4:5], v[192:193], v[76:77]
	v_add_u32_e32 v71, 0x4000, v71
	v_cvt_pk_bf16_f32 v78, v4, v5
	v_lshlrev_b32_e32 v76, 16, v160
	v_and_b32_e32 v77, 0xffff0000, v160
	global_store_dword v71, v78, s[6:7]
	v_pk_fma_f32 v[4:5], v[4:5], v[194:195], v[76:77]
	v_add_u32_e32 v71, 0x4000, v71
	v_cvt_pk_bf16_f32 v78, v4, v5
	v_lshlrev_b32_e32 v76, 16, v161
	v_and_b32_e32 v77, 0xffff0000, v161
	global_store_dword v71, v78, s[6:7]
	v_pk_fma_f32 v[4:5], v[4:5], v[196:197], v[76:77]
	v_add_u32_e32 v71, 0x4000, v71
	global_load_dword v150, v70, s[6:7]
	v_add_u32_e32 v70, 0x4000, v70
	global_load_dword v151, v70, s[6:7]
	v_add_u32_e32 v70, 0x4000, v70
	global_load_dword v152, v70, s[6:7]
	v_add_u32_e32 v70, 0x4000, v70
	global_load_dword v153, v70, s[6:7]
	v_add_u32_e32 v70, 0x4000, v70
	global_load_dword v154, v70, s[6:7]
	v_add_u32_e32 v70, 0x4000, v70
	global_load_dword v155, v70, s[6:7]
	v_add_u32_e32 v70, 0x4000, v70
	global_load_dword v156, v70, s[6:7]
	v_add_u32_e32 v70, 0x4000, v70
	global_load_dword v157, v70, s[6:7]
	v_add_u32_e32 v70, 0x4000, v70
	global_load_dword v158, v70, s[6:7]
	v_add_u32_e32 v70, 0x4000, v70
	global_load_dword v159, v70, s[6:7]
	v_add_u32_e32 v70, 0x4000, v70
	global_load_dword v160, v70, s[6:7]
	v_add_u32_e32 v70, 0x4000, v70
	global_load_dword v161, v70, s[6:7]
	v_add_u32_e32 v70, 0x4000, v70
	global_load_dwordx2 v[174:175], v72, s[6:7]
	global_load_dwordx2 v[176:177], v72, s[6:7] offset:256
	global_load_dwordx2 v[178:179], v72, s[6:7] offset:512
	global_load_dwordx2 v[180:181], v72, s[6:7] offset:768
	global_load_dwordx2 v[182:183], v72, s[6:7] offset:1024
	global_load_dwordx2 v[184:185], v72, s[6:7] offset:1280
	global_load_dwordx2 v[186:187], v72, s[6:7] offset:1536
	global_load_dwordx2 v[188:189], v72, s[6:7] offset:1792
	global_load_dwordx2 v[190:191], v72, s[6:7] offset:2048
	global_load_dwordx2 v[192:193], v72, s[6:7] offset:2304
	global_load_dwordx2 v[194:195], v72, s[6:7] offset:2560
	global_load_dwordx2 v[196:197], v72, s[6:7] offset:2816
	v_add_u32_e32 v72, 0xc00, v72
	s_waitcnt vmcnt(36)
	v_cvt_pk_bf16_f32 v78, v4, v5
	v_lshlrev_b32_e32 v76, 16, v80
	v_and_b32_e32 v77, 0xffff0000, v80
	global_store_dword v71, v78, s[6:7]
	v_pk_fma_f32 v[4:5], v[4:5], v[100:101], v[76:77]
	v_add_u32_e32 v71, 0x4000, v71
	v_cvt_pk_bf16_f32 v78, v4, v5
	v_lshlrev_b32_e32 v76, 16, v81
	v_and_b32_e32 v77, 0xffff0000, v81
	global_store_dword v71, v78, s[6:7]
	v_pk_fma_f32 v[4:5], v[4:5], v[102:103], v[76:77]
	v_add_u32_e32 v71, 0x4000, v71
	v_cvt_pk_bf16_f32 v78, v4, v5
	v_lshlrev_b32_e32 v76, 16, v82
	v_and_b32_e32 v77, 0xffff0000, v82
	global_store_dword v71, v78, s[6:7]
	v_pk_fma_f32 v[4:5], v[4:5], v[104:105], v[76:77]
	v_add_u32_e32 v71, 0x4000, v71
	v_cvt_pk_bf16_f32 v78, v4, v5
	v_lshlrev_b32_e32 v76, 16, v83
	v_and_b32_e32 v77, 0xffff0000, v83
	global_store_dword v71, v78, s[6:7]
	v_pk_fma_f32 v[4:5], v[4:5], v[106:107], v[76:77]
	v_add_u32_e32 v71, 0x4000, v71
	v_cvt_pk_bf16_f32 v78, v4, v5
	v_lshlrev_b32_e32 v76, 16, v84
	v_and_b32_e32 v77, 0xffff0000, v84
	global_store_dword v71, v78, s[6:7]
	v_pk_fma_f32 v[4:5], v[4:5], v[108:109], v[76:77]
	v_add_u32_e32 v71, 0x4000, v71
	v_cvt_pk_bf16_f32 v78, v4, v5
	v_lshlrev_b32_e32 v76, 16, v85
	v_and_b32_e32 v77, 0xffff0000, v85
	global_store_dword v71, v78, s[6:7]
	v_pk_fma_f32 v[4:5], v[4:5], v[110:111], v[76:77]
	v_add_u32_e32 v71, 0x4000, v71
	v_cvt_pk_bf16_f32 v78, v4, v5
	v_lshlrev_b32_e32 v76, 16, v86
	v_and_b32_e32 v77, 0xffff0000, v86
	global_store_dword v71, v78, s[6:7]
; __device__ __forceinline__ unsigned pk2(float lo, float hi) { f32x2 v = {lo, hi}; bf16x2_t b = __builtin_convertvector(v, bf16x2_t); return __builtin_bit_cast(unsigned, b); }
; __device__ __forceinline__ void gla_scan(bf16* U, const float* D, int gtid, int nthr) {
;     ...
;         for (int p0 = 0; p0 < NCH; p0 += 12) {
;             unsigned uu[12]; f32x2 dd[12];
; #pragma unroll
;             for (int i = 0; i < 12; ++i) { uu[i] = u[(size_t)(p0 + i) * 4096]; dd[i] = d[(p0 + i) * 32]; }
; #pragma unroll
;             for (int i = 0; i < 12; ++i) { u[(size_t)(p0 + i) * 4096] = pk2(S.x, S.y); S.x = dd[i].x * S.x + bflo(uu[i]); S.y = dd[i].y * S.y + bfhi(uu[i]); }
	v_pk_fma_f32 v[4:5], v[4:5], v[112:113], v[76:77]
	v_add_u32_e32 v71, 0x4000, v71
	v_cvt_pk_bf16_f32 v78, v4, v5
	v_lshlrev_b32_e32 v76, 16, v87
	v_and_b32_e32 v77, 0xffff0000, v87
	global_store_dword v71, v78, s[6:7]
	v_pk_fma_f32 v[4:5], v[4:5], v[114:115], v[76:77]
	v_add_u32_e32 v71, 0x4000, v71
	v_cvt_pk_bf16_f32 v78, v4, v5
	v_lshlrev_b32_e32 v76, 16, v88
	v_and_b32_e32 v77, 0xffff0000, v88
	global_store_dword v71, v78, s[6:7]
	v_pk_fma_f32 v[4:5], v[4:5], v[116:117], v[76:77]
	v_add_u32_e32 v71, 0x4000, v71
	v_cvt_pk_bf16_f32 v78, v4, v5
	v_lshlrev_b32_e32 v76, 16, v89
	v_and_b32_e32 v77, 0xffff0000, v89
	global_store_dword v71, v78, s[6:7]
	v_pk_fma_f32 v[4:5], v[4:5], v[118:119], v[76:77]
	v_add_u32_e32 v71, 0x4000, v71
	v_cvt_pk_bf16_f32 v78, v4, v5
	v_lshlrev_b32_e32 v76, 16, v90
	v_and_b32_e32 v77, 0xffff0000, v90
	global_store_dword v71, v78, s[6:7]
	v_pk_fma_f32 v[4:5], v[4:5], v[120:121], v[76:77]
	v_add_u32_e32 v71, 0x4000, v71
	v_cvt_pk_bf16_f32 v78, v4, v5
	v_lshlrev_b32_e32 v76, 16, v91
	v_and_b32_e32 v77, 0xffff0000, v91
	global_store_dword v71, v78, s[6:7]
	v_pk_fma_f32 v[4:5], v[4:5], v[122:123], v[76:77]
	v_add_u32_e32 v71, 0x4000, v71
	global_load_dword v80, v70, s[6:7]
	v_add_u32_e32 v70, 0x4000, v70
	global_load_dword v81, v70, s[6:7]
	v_add_u32_e32 v70, 0x4000, v70
	global_load_dword v82, v70, s[6:7]
	v_add_u32_e32 v70, 0x4000, v70
	global_load_dword v83, v70, s[6:7]
	v_add_u32_e32 v70, 0x4000, v70
	global_load_dword v84, v70, s[6:7]
	v_add_u32_e32 v70, 0x4000, v70
	global_load_dword v85, v70, s[6:7]
	v_add_u32_e32 v70, 0x4000, v70
	global_load_dword v86, v70, s[6:7]
	v_add_u32_e32 v70, 0x4000, v70
	global_load_dword v87, v70, s[6:7]
	v_add_u32_e32 v70, 0x4000, v70
	global_load_dword v88, v70, s[6:7]
	v_add_u32_e32 v70, 0x4000, v70
	global_load_dword v89, v70, s[6:7]
	v_add_u32_e32 v70, 0x4000, v70
	global_load_dword v90, v70, s[6:7]
	v_add_u32_e32 v70, 0x4000, v70
	global_load_dword v91, v70, s[6:7]
	v_add_u32_e32 v70, 0x4000, v70
	global_load_dwordx2 v[100:101], v72, s[6:7]
	global_load_dwordx2 v[102:103], v72, s[6:7] offset:256
	global_load_dwordx2 v[104:105], v72, s[6:7] offset:512
	global_load_dwordx2 v[106:107], v72, s[6:7] offset:768
	global_load_dwordx2 v[108:109], v72, s[6:7] offset:1024
	global_load_dwordx2 v[110:111], v72, s[6:7] offset:1280
	global_load_dwordx2 v[112:113], v72, s[6:7] offset:1536
	global_load_dwordx2 v[114:115], v72, s[6:7] offset:1792
	global_load_dwordx2 v[116:117], v72, s[6:7] offset:2048
	global_load_dwordx2 v[118:119], v72, s[6:7] offset:2304
	global_load_dwordx2 v[120:121], v72, s[6:7] offset:2560
	global_load_dwordx2 v[122:123], v72, s[6:7] offset:2816
	v_add_u32_e32 v72, 0xc00, v72
	s_waitcnt vmcnt(36)
	v_cvt_pk_bf16_f32 v78, v4, v5
	v_lshlrev_b32_e32 v76, 16, v150
	v_and_b32_e32 v77, 0xffff0000, v150
	global_store_dword v71, v78, s[6:7]
	v_pk_fma_f32 v[4:5], v[4:5], v[174:175], v[76:77]
	v_add_u32_e32 v71, 0x4000, v71
	v_cvt_pk_bf16_f32 v78, v4, v5
	v_lshlrev_b32_e32 v76, 16, v151
	v_and_b32_e32 v77, 0xffff0000, v151
	global_store_dword v71, v78, s[6:7]
	v_pk_fma_f32 v[4:5], v[4:5], v[176:177], v[76:77]
	v_add_u32_e32 v71, 0x4000, v71
	v_cvt_pk_bf16_f32 v78, v4, v5
	v_lshlrev_b32_e32 v76, 16, v152
	v_and_b32_e32 v77, 0xffff0000, v152
	global_store_dword v71, v78, s[6:7]
	v_pk_fma_f32 v[4:5], v[4:5], v[178:179], v[76:77]
	v_add_u32_e32 v71, 0x4000, v71
	v_cvt_pk_bf16_f32 v78, v4, v5
	v_lshlrev_b32_e32 v76, 16, v153
	v_and_b32_e32 v77, 0xffff0000, v153
	global_store_dword v71, v78, s[6:7]
	v_pk_fma_f32 v[4:5], v[4:5], v[180:181], v[76:77]
	v_add_u32_e32 v71, 0x4000, v71
	v_cvt_pk_bf16_f32 v78, v4, v5
	v_lshlrev_b32_e32 v76, 16, v154
	v_and_b32_e32 v77, 0xffff0000, v154
	global_store_dword v71, v78, s[6:7]
	v_pk_fma_f32 v[4:5], v[4:5], v[182:183], v[76:77]
	v_add_u32_e32 v71, 0x4000, v71
	v_cvt_pk_bf16_f32 v78, v4, v5
	v_lshlrev_b32_e32 v76, 16, v155
	v_and_b32_e32 v77, 0xffff0000, v155
	global_store_dword v71, v78, s[6:7]
	v_pk_fma_f32 v[4:5], v[4:5], v[184:185], v[76:77]
	v_add_u32_e32 v71, 0x4000, v71
	v_cvt_pk_bf16_f32 v78, v4, v5
	v_lshlrev_b32_e32 v76, 16, v156
	v_and_b32_e32 v77, 0xffff0000, v156
	global_store_dword v71, v78, s[6:7]
	v_pk_fma_f32 v[4:5], v[4:5], v[186:187], v[76:77]
	v_add_u32_e32 v71, 0x4000, v71
	v_cvt_pk_bf16_f32 v78, v4, v5
	v_lshlrev_b32_e32 v76, 16, v157
	v_and_b32_e32 v77, 0xffff0000, v157
	global_store_dword v71, v78, s[6:7]
	v_pk_fma_f32 v[4:5], v[4:5], v[188:189], v[76:77]
	v_add_u32_e32 v71, 0x4000, v71
	v_cvt_pk_bf16_f32 v78, v4, v5
	v_lshlrev_b32_e32 v76, 16, v158
	v_and_b32_e32 v77, 0xffff0000, v158
	global_store_dword v71, v78, s[6:7]
	v_pk_fma_f32 v[4:5], v[4:5], v[190:191], v[76:77]
	v_add_u32_e32 v71, 0x4000, v71
	v_cvt_pk_bf16_f32 v78, v4, v5
	v_lshlrev_b32_e32 v76, 16, v159
	v_and_b32_e32 v77, 0xffff0000, v159
	global_store_dword v71, v78, s[6:7]
	v_pk_fma_f32 v[4:5], v[4:5], v[192:193], v[76:77]
	v_add_u32_e32 v71, 0x4000, v71
	v_cvt_pk_bf16_f32 v78, v4, v5
	v_lshlrev_b32_e32 v76, 16, v160
	v_and_b32_e32 v77, 0xffff0000, v160
	global_store_dword v71, v78, s[6:7]
	v_pk_fma_f32 v[4:5], v[4:5], v[194:195], v[76:77]
	v_add_u32_e32 v71, 0x4000, v71
	v_cvt_pk_bf16_f32 v78, v4, v5
	v_lshlrev_b32_e32 v76, 16, v161
	v_and_b32_e32 v77, 0xffff0000, v161
	global_store_dword v71, v78, s[6:7]
	v_pk_fma_f32 v[4:5], v[4:5], v[196:197], v[76:77]
	v_add_u32_e32 v71, 0x4000, v71
	global_load_dword v150, v70, s[6:7]
	v_add_u32_e32 v70, 0x4000, v70
	global_load_dword v151, v70, s[6:7]
	v_add_u32_e32 v70, 0x4000, v70
	global_load_dword v152, v70, s[6:7]
	v_add_u32_e32 v70, 0x4000, v70
	global_load_dword v153, v70, s[6:7]
	v_add_u32_e32 v70, 0x4000, v70
	global_load_dword v154, v70, s[6:7]
	v_add_u32_e32 v70, 0x4000, v70
	global_load_dword v155, v70, s[6:7]
	v_add_u32_e32 v70, 0x4000, v70
	global_load_dword v156, v70, s[6:7]
	v_add_u32_e32 v70, 0x4000, v70
	global_load_dword v157, v70, s[6:7]
	v_add_u32_e32 v70, 0x4000, v70
	global_load_dword v158, v70, s[6:7]
	v_add_u32_e32 v70, 0x4000, v70
	global_load_dword v159, v70, s[6:7]
	v_add_u32_e32 v70, 0x4000, v70
	global_load_dword v160, v70, s[6:7]
	v_add_u32_e32 v70, 0x4000, v70
	global_load_dword v161, v70, s[6:7]
	v_add_u32_e32 v70, 0x4000, v70
	global_load_dwordx2 v[174:175], v72, s[6:7]
	global_load_dwordx2 v[176:177], v72, s[6:7] offset:256
	global_load_dwordx2 v[178:179], v72, s[6:7] offset:512
	global_load_dwordx2 v[180:181], v72, s[6:7] offset:768
	global_load_dwordx2 v[182:183], v72, s[6:7] offset:1024
	global_load_dwordx2 v[184:185], v72, s[6:7] offset:1280
	global_load_dwordx2 v[186:187], v72, s[6:7] offset:1536
	global_load_dwordx2 v[188:189], v72, s[6:7] offset:1792
	global_load_dwordx2 v[190:191], v72, s[6:7] offset:2048
	global_load_dwordx2 v[192:193], v72, s[6:7] offset:2304
	global_load_dwordx2 v[194:195], v72, s[6:7] offset:2560
	global_load_dwordx2 v[196:197], v72, s[6:7] offset:2816
	v_add_u32_e32 v72, 0xc00, v72
	s_waitcnt vmcnt(36)
; __device__ __forceinline__ unsigned pk2(float lo, float hi) { f32x2 v = {lo, hi}; bf16x2_t b = __builtin_convertvector(v, bf16x2_t); return __builtin_bit_cast(unsigned, b); }
; __device__ __forceinline__ void gla_scan(bf16* U, const float* D, int gtid, int nthr) {
;     ...
;         for (int p0 = 0; p0 < NCH; p0 += 12) {
;             unsigned uu[12]; f32x2 dd[12];
; #pragma unroll
;             for (int i = 0; i < 12; ++i) { uu[i] = u[(size_t)(p0 + i) * 4096]; dd[i] = d[(p0 + i) * 32]; }
; #pragma unroll
;             for (int i = 0; i < 12; ++i) { u[(size_t)(p0 + i) * 4096] = pk2(S.x, S.y); S.x = dd[i].x * S.x + bflo(uu[i]); S.y = dd[i].y * S.y + bfhi(uu[i]); }
	v_cvt_pk_bf16_f32 v78, v4, v5
	v_lshlrev_b32_e32 v76, 16, v80
	v_and_b32_e32 v77, 0xffff0000, v80
	global_store_dword v71, v78, s[6:7]
	v_pk_fma_f32 v[4:5], v[4:5], v[100:101], v[76:77]
	v_add_u32_e32 v71, 0x4000, v71
	v_cvt_pk_bf16_f32 v78, v4, v5
	v_lshlrev_b32_e32 v76, 16, v81
	v_and_b32_e32 v77, 0xffff0000, v81
	global_store_dword v71, v78, s[6:7]
	v_pk_fma_f32 v[4:5], v[4:5], v[102:103], v[76:77]
	v_add_u32_e32 v71, 0x4000, v71
	v_cvt_pk_bf16_f32 v78, v4, v5
	v_lshlrev_b32_e32 v76, 16, v82
	v_and_b32_e32 v77, 0xffff0000, v82
	global_store_dword v71, v78, s[6:7]
	v_pk_fma_f32 v[4:5], v[4:5], v[104:105], v[76:77]
	v_add_u32_e32 v71, 0x4000, v71
	v_cvt_pk_bf16_f32 v78, v4, v5
	v_lshlrev_b32_e32 v76, 16, v83
	v_and_b32_e32 v77, 0xffff0000, v83
	global_store_dword v71, v78, s[6:7]
	v_pk_fma_f32 v[4:5], v[4:5], v[106:107], v[76:77]
	v_add_u32_e32 v71, 0x4000, v71
	v_cvt_pk_bf16_f32 v78, v4, v5
	v_lshlrev_b32_e32 v76, 16, v84
	v_and_b32_e32 v77, 0xffff0000, v84
	global_store_dword v71, v78, s[6:7]
	v_pk_fma_f32 v[4:5], v[4:5], v[108:109], v[76:77]
	v_add_u32_e32 v71, 0x4000, v71
	v_cvt_pk_bf16_f32 v78, v4, v5
	v_lshlrev_b32_e32 v76, 16, v85
	v_and_b32_e32 v77, 0xffff0000, v85
	global_store_dword v71, v78, s[6:7]
	v_pk_fma_f32 v[4:5], v[4:5], v[110:111], v[76:77]
	v_add_u32_e32 v71, 0x4000, v71
	v_cvt_pk_bf16_f32 v78, v4, v5
	v_lshlrev_b32_e32 v76, 16, v86
	v_and_b32_e32 v77, 0xffff0000, v86
	global_store_dword v71, v78, s[6:7]
	v_pk_fma_f32 v[4:5], v[4:5], v[112:113], v[76:77]
	v_add_u32_e32 v71, 0x4000, v71
	v_cvt_pk_bf16_f32 v78, v4, v5
	v_lshlrev_b32_e32 v76, 16, v87
	v_and_b32_e32 v77, 0xffff0000, v87
	global_store_dword v71, v78, s[6:7]
	v_pk_fma_f32 v[4:5], v[4:5], v[114:115], v[76:77]
	v_add_u32_e32 v71, 0x4000, v71
	v_cvt_pk_bf16_f32 v78, v4, v5
	v_lshlrev_b32_e32 v76, 16, v88
	v_and_b32_e32 v77, 0xffff0000, v88
	global_store_dword v71, v78, s[6:7]
	v_pk_fma_f32 v[4:5], v[4:5], v[116:117], v[76:77]
	v_add_u32_e32 v71, 0x4000, v71
	v_cvt_pk_bf16_f32 v78, v4, v5
	v_lshlrev_b32_e32 v76, 16, v89
	v_and_b32_e32 v77, 0xffff0000, v89
	global_store_dword v71, v78, s[6:7]
	v_pk_fma_f32 v[4:5], v[4:5], v[118:119], v[76:77]
	v_add_u32_e32 v71, 0x4000, v71
	v_cvt_pk_bf16_f32 v78, v4, v5
	v_lshlrev_b32_e32 v76, 16, v90
	v_and_b32_e32 v77, 0xffff0000, v90
	global_store_dword v71, v78, s[6:7]
	v_pk_fma_f32 v[4:5], v[4:5], v[120:121], v[76:77]
	v_add_u32_e32 v71, 0x4000, v71
	v_cvt_pk_bf16_f32 v78, v4, v5
	v_lshlrev_b32_e32 v76, 16, v91
	v_and_b32_e32 v77, 0xffff0000, v91
	global_store_dword v71, v78, s[6:7]
	v_pk_fma_f32 v[4:5], v[4:5], v[122:123], v[76:77]
	v_add_u32_e32 v71, 0x4000, v71
	global_load_dword v80, v70, s[6:7]
	v_add_u32_e32 v70, 0x4000, v70
	global_load_dword v81, v70, s[6:7]
	v_add_u32_e32 v70, 0x4000, v70
	global_load_dword v82, v70, s[6:7]
	v_add_u32_e32 v70, 0x4000, v70
	global_load_dword v83, v70, s[6:7]
	v_add_u32_e32 v70, 0x4000, v70
	global_load_dword v84, v70, s[6:7]
	v_add_u32_e32 v70, 0x4000, v70
	global_load_dword v85, v70, s[6:7]
	v_add_u32_e32 v70, 0x4000, v70
	global_load_dword v86, v70, s[6:7]
	v_add_u32_e32 v70, 0x4000, v70
	global_load_dword v87, v70, s[6:7]
	v_add_u32_e32 v70, 0x4000, v70
	global_load_dword v88, v70, s[6:7]
	v_add_u32_e32 v70, 0x4000, v70
	global_load_dword v89, v70, s[6:7]
	v_add_u32_e32 v70, 0x4000, v70
	global_load_dword v90, v70, s[6:7]
	v_add_u32_e32 v70, 0x4000, v70
	global_load_dword v91, v70, s[6:7]
	v_add_u32_e32 v70, 0x4000, v70
	global_load_dwordx2 v[100:101], v72, s[6:7]
	global_load_dwordx2 v[102:103], v72, s[6:7] offset:256
	global_load_dwordx2 v[104:105], v72, s[6:7] offset:512
	global_load_dwordx2 v[106:107], v72, s[6:7] offset:768
	global_load_dwordx2 v[108:109], v72, s[6:7] offset:1024
	global_load_dwordx2 v[110:111], v72, s[6:7] offset:1280
	global_load_dwordx2 v[112:113], v72, s[6:7] offset:1536
	global_load_dwordx2 v[114:115], v72, s[6:7] offset:1792
	global_load_dwordx2 v[116:117], v72, s[6:7] offset:2048
	global_load_dwordx2 v[118:119], v72, s[6:7] offset:2304
	global_load_dwordx2 v[120:121], v72, s[6:7] offset:2560
	global_load_dwordx2 v[122:123], v72, s[6:7] offset:2816
	v_add_u32_e32 v72, 0xc00, v72
	s_waitcnt vmcnt(36)
; __device__ __forceinline__ unsigned pk2(float lo, float hi) { f32x2 v = {lo, hi}; bf16x2_t b = __builtin_convertvector(v, bf16x2_t); return __builtin_bit_cast(unsigned, b); }
; __device__ __forceinline__ void gla_scan(bf16* U, const float* D, int gtid, int nthr) {
;     for (int idx = gtid; idx < 24 * 4096; idx += nthr) {
;         const int chain = idx >> 12, e = (idx & 4095) * 2, dk = e & 63;
;         unsigned* u = (unsigned*)(U + (size_t)chain * NCH * 8192 + e); const f32x2* d = (const f32x2*)(D + (size_t)chain * NCH * 64 + dk); f32x2 S = (f32x2){0.f, 0.f};
;         for (int p0 = 0; p0 < NCH; p0 += 12) {
;             unsigned uu[12]; f32x2 dd[12];
; #pragma unroll
;             for (int i = 0; i < 12; ++i) { uu[i] = u[(size_t)(p0 + i) * 4096]; dd[i] = d[(p0 + i) * 32]; }
; #pragma unroll
;             for (int i = 0; i < 12; ++i) { u[(size_t)(p0 + i) * 4096] = pk2(S.x, S.y); S.x = dd[i].x * S.x + bflo(uu[i]); S.y = dd[i].y * S.y + bfhi(uu[i]); }
	v_cvt_pk_bf16_f32 v78, v4, v5
	v_lshlrev_b32_e32 v76, 16, v150
	v_and_b32_e32 v77, 0xffff0000, v150
	global_store_dword v71, v78, s[6:7]
	v_pk_fma_f32 v[4:5], v[4:5], v[174:175], v[76:77]
	v_add_u32_e32 v71, 0x4000, v71
	v_cvt_pk_bf16_f32 v78, v4, v5
	v_lshlrev_b32_e32 v76, 16, v151
	v_and_b32_e32 v77, 0xffff0000, v151
	global_store_dword v71, v78, s[6:7]
	v_pk_fma_f32 v[4:5], v[4:5], v[176:177], v[76:77]
	v_add_u32_e32 v71, 0x4000, v71
	v_cvt_pk_bf16_f32 v78, v4, v5
	v_lshlrev_b32_e32 v76, 16, v152
	v_and_b32_e32 v77, 0xffff0000, v152
	global_store_dword v71, v78, s[6:7]
	v_pk_fma_f32 v[4:5], v[4:5], v[178:179], v[76:77]
	v_add_u32_e32 v71, 0x4000, v71
	v_cvt_pk_bf16_f32 v78, v4, v5
	v_lshlrev_b32_e32 v76, 16, v153
	v_and_b32_e32 v77, 0xffff0000, v153
	global_store_dword v71, v78, s[6:7]
	v_pk_fma_f32 v[4:5], v[4:5], v[180:181], v[76:77]
	v_add_u32_e32 v71, 0x4000, v71
	v_cvt_pk_bf16_f32 v78, v4, v5
	v_lshlrev_b32_e32 v76, 16, v154
	v_and_b32_e32 v77, 0xffff0000, v154
	global_store_dword v71, v78, s[6:7]
	v_pk_fma_f32 v[4:5], v[4:5], v[182:183], v[76:77]
	v_add_u32_e32 v71, 0x4000, v71
	v_cvt_pk_bf16_f32 v78, v4, v5
	v_lshlrev_b32_e32 v76, 16, v155
	v_and_b32_e32 v77, 0xffff0000, v155
	global_store_dword v71, v78, s[6:7]
	v_pk_fma_f32 v[4:5], v[4:5], v[184:185], v[76:77]
	v_add_u32_e32 v71, 0x4000, v71
	v_cvt_pk_bf16_f32 v78, v4, v5
	v_lshlrev_b32_e32 v76, 16, v156
	v_and_b32_e32 v77, 0xffff0000, v156
	global_store_dword v71, v78, s[6:7]
	v_pk_fma_f32 v[4:5], v[4:5], v[186:187], v[76:77]
	v_add_u32_e32 v71, 0x4000, v71
	v_cvt_pk_bf16_f32 v78, v4, v5
	v_lshlrev_b32_e32 v76, 16, v157
	v_and_b32_e32 v77, 0xffff0000, v157
	global_store_dword v71, v78, s[6:7]
	v_pk_fma_f32 v[4:5], v[4:5], v[188:189], v[76:77]
	v_add_u32_e32 v71, 0x4000, v71
	v_cvt_pk_bf16_f32 v78, v4, v5
	v_lshlrev_b32_e32 v76, 16, v158
	v_and_b32_e32 v77, 0xffff0000, v158
	global_store_dword v71, v78, s[6:7]
	v_pk_fma_f32 v[4:5], v[4:5], v[190:191], v[76:77]
	v_add_u32_e32 v71, 0x4000, v71
	v_cvt_pk_bf16_f32 v78, v4, v5
	v_lshlrev_b32_e32 v76, 16, v159
	v_and_b32_e32 v77, 0xffff0000, v159
	global_store_dword v71, v78, s[6:7]
	v_pk_fma_f32 v[4:5], v[4:5], v[192:193], v[76:77]
	v_add_u32_e32 v71, 0x4000, v71
	v_cvt_pk_bf16_f32 v78, v4, v5
	v_lshlrev_b32_e32 v76, 16, v160
	v_and_b32_e32 v77, 0xffff0000, v160
	global_store_dword v71, v78, s[6:7]
	v_pk_fma_f32 v[4:5], v[4:5], v[194:195], v[76:77]
	v_add_u32_e32 v71, 0x4000, v71
	v_cvt_pk_bf16_f32 v78, v4, v5
	v_lshlrev_b32_e32 v76, 16, v161
	v_and_b32_e32 v77, 0xffff0000, v161
	global_store_dword v71, v78, s[6:7]
	v_pk_fma_f32 v[4:5], v[4:5], v[196:197], v[76:77]
	v_add_u32_e32 v71, 0x4000, v71
	s_waitcnt vmcnt(12)
	v_cvt_pk_bf16_f32 v78, v4, v5
	v_lshlrev_b32_e32 v76, 16, v80
	v_and_b32_e32 v77, 0xffff0000, v80
	global_store_dword v71, v78, s[6:7]
	v_pk_fma_f32 v[4:5], v[4:5], v[100:101], v[76:77]
	v_add_u32_e32 v71, 0x4000, v71
	v_cvt_pk_bf16_f32 v78, v4, v5
	v_lshlrev_b32_e32 v76, 16, v81
	v_and_b32_e32 v77, 0xffff0000, v81
	global_store_dword v71, v78, s[6:7]
	v_pk_fma_f32 v[4:5], v[4:5], v[102:103], v[76:77]
	v_add_u32_e32 v71, 0x4000, v71
	v_cvt_pk_bf16_f32 v78, v4, v5
	v_lshlrev_b32_e32 v76, 16, v82
	v_and_b32_e32 v77, 0xffff0000, v82
	global_store_dword v71, v78, s[6:7]
	v_pk_fma_f32 v[4:5], v[4:5], v[104:105], v[76:77]
	v_add_u32_e32 v71, 0x4000, v71
	v_cvt_pk_bf16_f32 v78, v4, v5
	v_lshlrev_b32_e32 v76, 16, v83
	v_and_b32_e32 v77, 0xffff0000, v83
	global_store_dword v71, v78, s[6:7]
	v_pk_fma_f32 v[4:5], v[4:5], v[106:107], v[76:77]
	v_add_u32_e32 v71, 0x4000, v71
	v_cvt_pk_bf16_f32 v78, v4, v5
	v_lshlrev_b32_e32 v76, 16, v84
	v_and_b32_e32 v77, 0xffff0000, v84
	global_store_dword v71, v78, s[6:7]
	v_pk_fma_f32 v[4:5], v[4:5], v[108:109], v[76:77]
	v_add_u32_e32 v71, 0x4000, v71
	v_cvt_pk_bf16_f32 v78, v4, v5
	v_lshlrev_b32_e32 v76, 16, v85
	v_and_b32_e32 v77, 0xffff0000, v85
	global_store_dword v71, v78, s[6:7]
	v_pk_fma_f32 v[4:5], v[4:5], v[110:111], v[76:77]
	v_add_u32_e32 v71, 0x4000, v71
	v_cvt_pk_bf16_f32 v78, v4, v5
	v_lshlrev_b32_e32 v76, 16, v86
	v_and_b32_e32 v77, 0xffff0000, v86
	global_store_dword v71, v78, s[6:7]
	v_pk_fma_f32 v[4:5], v[4:5], v[112:113], v[76:77]
	v_add_u32_e32 v71, 0x4000, v71
	v_cvt_pk_bf16_f32 v78, v4, v5
	v_lshlrev_b32_e32 v76, 16, v87
	v_and_b32_e32 v77, 0xffff0000, v87
	global_store_dword v71, v78, s[6:7]
	v_pk_fma_f32 v[4:5], v[4:5], v[114:115], v[76:77]
	v_add_u32_e32 v71, 0x4000, v71
	v_cvt_pk_bf16_f32 v78, v4, v5
	v_lshlrev_b32_e32 v76, 16, v88
	v_and_b32_e32 v77, 0xffff0000, v88
	global_store_dword v71, v78, s[6:7]
	v_pk_fma_f32 v[4:5], v[4:5], v[116:117], v[76:77]
	v_add_u32_e32 v71, 0x4000, v71
	v_cvt_pk_bf16_f32 v78, v4, v5
	v_lshlrev_b32_e32 v76, 16, v89
	v_and_b32_e32 v77, 0xffff0000, v89
	global_store_dword v71, v78, s[6:7]
	v_pk_fma_f32 v[4:5], v[4:5], v[118:119], v[76:77]
	v_add_u32_e32 v71, 0x4000, v71
	v_cvt_pk_bf16_f32 v78, v4, v5
	v_lshlrev_b32_e32 v76, 16, v90
	v_and_b32_e32 v77, 0xffff0000, v90
	global_store_dword v71, v78, s[6:7]
	v_pk_fma_f32 v[4:5], v[4:5], v[120:121], v[76:77]
	v_add_u32_e32 v71, 0x4000, v71
	v_cvt_pk_bf16_f32 v78, v4, v5
	v_lshlrev_b32_e32 v76, 16, v91
	v_and_b32_e32 v77, 0xffff0000, v91
	global_store_dword v71, v78, s[6:7]
	v_pk_fma_f32 v[4:5], v[4:5], v[122:123], v[76:77]
	v_add_u32_e32 v71, 0x4000, v71
	v_readlane_b32 s2, v244, 57
	s_nop 1
	v_add_u32_e32 v34, s2, v34
	s_mov_b32 s2, 0x17fff
	v_cmp_lt_i32_e32 vcc, s2, v34
	v_readlane_b32 s2, v243, 45
	s_or_b64 s[10:11], vcc, s[10:11]
	s_nop 0
	v_add_u32_e32 v36, s2, v36
	s_andn2_b64 exec, exec, s[10:11]
	s_cbranch_execnz .LBB0_600
	s_or_b64 exec, exec, s[10:11]
